# dilated attention full-tile path: 8 K fragments read up front with counted lgkmcnt (on top of the sliding-window batching)
# baseline (speedup 1.0000x reference)
.Lm1_full:
	v_add_u32_e32 v152, 0, v216
	ds_read_b128 v[48:51], v152
	ds_read_b128 v[52:55], v152 offset:2080
	ds_read_b128 v[56:59], v152 offset:4160
	ds_read_b128 v[60:63], v152 offset:6240
	ds_read_b128 v[218:221], v152 offset:512
	ds_read_b128 v[222:225], v152 offset:2592
	ds_read_b128 v[232:235], v152 offset:4672
	ds_read_b128 v[244:247], v152 offset:6752
	v_cmp_neq_f32_e32 vcc, 0, v212
	s_waitcnt lgkmcnt(7)
	v_mfma_f32_32x32x16_bf16 v[32:47], v[48:51], v[140:143], 0
	s_waitcnt lgkmcnt(6)
	v_mfma_f32_32x32x16_bf16 v[32:47], v[52:55], v[136:139], v[32:47]
	s_waitcnt lgkmcnt(5)
	v_mfma_f32_32x32x16_bf16 v[32:47], v[56:59], v[132:135], v[32:47]
	s_waitcnt lgkmcnt(4)
	v_mfma_f32_32x32x16_bf16 v[32:47], v[60:63], v[128:131], v[32:47]
	s_waitcnt lgkmcnt(3)
	v_mfma_f32_32x32x16_bf16 v[48:63], v[218:221], v[140:143], 0
	s_waitcnt lgkmcnt(2)
	v_mfma_f32_32x32x16_bf16 v[48:63], v[222:225], v[136:139], v[48:63]
	s_waitcnt lgkmcnt(1)
	v_mfma_f32_32x32x16_bf16 v[48:63], v[232:235], v[132:135], v[48:63]
	s_waitcnt lgkmcnt(0)
	v_mfma_f32_32x32x16_bf16 v[48:63], v[244:247], v[128:131], v[48:63]
	s_cbranch_vccz .LBB0_395
	s_nop 7
	v_sub_f32_e32 v47, v47, v212
	v_sub_f32_e32 v46, v46, v212
	v_sub_f32_e32 v45, v45, v212
	v_sub_f32_e32 v44, v44, v212
	v_sub_f32_e32 v43, v43, v212
	v_sub_f32_e32 v42, v42, v212
	v_sub_f32_e32 v41, v41, v212
	v_sub_f32_e32 v40, v40, v212
	v_sub_f32_e32 v39, v39, v212
	v_sub_f32_e32 v38, v38, v212
	v_sub_f32_e32 v37, v37, v212
	v_sub_f32_e32 v36, v36, v212
	v_sub_f32_e32 v35, v35, v212
	v_sub_f32_e32 v34, v34, v212
	v_sub_f32_e32 v33, v33, v212
	v_sub_f32_e32 v32, v32, v212
	v_sub_f32_e32 v63, v63, v212
	v_sub_f32_e32 v62, v62, v212
	v_sub_f32_e32 v61, v61, v212
	v_sub_f32_e32 v60, v60, v212
	v_sub_f32_e32 v59, v59, v212
	v_sub_f32_e32 v58, v58, v212
	v_sub_f32_e32 v57, v57, v212
	v_sub_f32_e32 v56, v56, v212
	v_sub_f32_e32 v55, v55, v212
	v_sub_f32_e32 v54, v54, v212
	v_sub_f32_e32 v53, v53, v212
	v_sub_f32_e32 v52, v52, v212
	v_sub_f32_e32 v51, v51, v212
	v_sub_f32_e32 v50, v50, v212
	v_sub_f32_e32 v49, v49, v212
	v_sub_f32_e32 v48, v48, v212
